# split packed v_pk_add_f32/v_pk_mul_f32 in the P5/P10 attention tile loops into scalar halves (bit-identical) on top of F
# speedup vs baseline: 1.0036x; 1.0036x over previous
;     ...
;     auto compute = [&](int buf, int t) {
;         const LAS bf16* Ks = (const LAS bf16*)(lds + koff(buf)); const LAS bf16* VT = (const LAS bf16*)(lds + voff(buf));
;         bf16x8 kf[2][4]; float bias[2][2][4];
; #pragma unroll
;         for (int kb = 0; kb < 2; ++kb)
; #pragma unroll
;             for (int ks = 0; ks < 4; ++ks) kf[kb][ks] = *(const LAS bf16x8*)(Ks + (32 * kh + 16 * kb + fr) * QP + 32 * ks + 8 * fq);
;         if (MODE == 0) { const LAS float* bp = BT + (2047 - 16 - (q0 + 32 * rp + fr - t * 64 - 32 * kh - 4 * fq));
; #pragma unroll
;                 for (int kb = 0; kb < 2; ++kb)
; #pragma unroll
;                     for (int i = 0; i < 4; ++i) bias[0][kb][i] = bp[16 * (kb + 1) + i]; }
;         __builtin_amdgcn_sched_barrier(0);
;         f32x4 s[2][2];
; #pragma unroll
;         for (int rb = 0; rb < 2; ++rb)
; #pragma unroll
;             for (int kb = 0; kb < 2; ++kb) s[rb][kb] = (f32x4){0.f, 0.f, 0.f, 0.f};
;         bf16x8 pf[2];
;         auto smax = [&](int rb) {
;             if (MODE == 0) { s[rb][0] = s[rb][0] + (f32x4){bias[rb][0][0], bias[rb][0][1], bias[rb][0][2], bias[rb][0][3]}; s[rb][1] = s[rb][1] + (f32x4){bias[rb][1][0], bias[rb][1][1], bias[rb][1][2], bias[rb][1][3]}; }
;             else { s[rb][0] = s[rb][0] - bref; s[rb][1] = s[rb][1] - bref; }
;             float ps = 0.f;
; #pragma unroll
;             for (int kb = 0; kb < 2; ++kb)
; #pragma unroll
;                 for (int i = 0; i < 4; ++i) { s[rb][kb][i] = __builtin_amdgcn_exp2f(s[rb][kb][i]); ps += s[rb][kb][i]; }
;             lrun[rb] += ps;
;             u32x4 pw; pw.x = pk2(s[rb][0][0], s[rb][0][1]); pw.y = pk2(s[rb][0][2], s[rb][0][3]); pw.z = pk2(s[rb][1][0], s[rb][1][1]); pw.w = pk2(s[rb][1][2], s[rb][1][3]);
;             pf[rb] = __builtin_bit_cast(bf16x8, pw); };
; #pragma unroll
;         for (int ks = 0; ks < 4; ++ks)
; #pragma unroll
;             for (int kb = 0; kb < 2; ++kb) MMA16(kf[kb][ks], qf[0][ks], s[0][kb]);
;         __builtin_amdgcn_sched_barrier(0);
;         bf16x8 vf[8];
; #pragma unroll
;         for (int db = 0; db < 8; ++db) vf[db] = *(const LAS bf16x8*)(VT + (16 * db + fr) * VPA + 32 * kh + 8 * fq);
;         if (MODE == 0) { const LAS float* bp = BT + (2047 - 16 - (q0 + 32 * rp + fr - t * 64 - 32 * kh - 4 * fq));
; #pragma unroll
;             for (int kb = 0; kb < 2; ++kb)
; #pragma unroll
.LBB0_58:
	v_add_f32_e32 v132, 0, v172
	v_add_f32_e32 v133, 0, v173
	ds_read_b128 v[172:175], v209 offset:55488
	v_add_f32_e32 v132, v170, v132
	v_add_f32_e32 v133, v171, v133
	ds_read_b128 v[136:139], v209 offset:59904
	v_add_f32_e32 v132, v150, v132
	v_add_f32_e32 v133, v151, v133
	ds_read_b128 v[182:185], v209 offset:60032
	v_add_f32_e32 v132, v148, v132
	v_add_f32_e32 v133, v149, v133
	ds_read_b128 v[148:151], v209 offset:55424
	v_add_f32_e32 v132, v146, v132
	v_add_f32_e32 v133, v147, v133
	ds_read_b128 v[188:191], v209 offset:60096
	v_add_f32_e32 v132, v144, v132
	v_add_f32_e32 v133, v145, v133
	ds_read_b128 v[144:147], v209 offset:59968
	v_add_f32_e32 v132, v142, v132
	v_add_f32_e32 v133, v143, v133
	s_nop 0
	v_add_f32_e32 v132, v140, v132
	v_add_f32_e32 v133, v141, v133
	ds_read_b128 v[140:143], v209 offset:55360
	v_add_f32_e32 v168, v168, v132
	v_add_f32_e32 v169, v169, v133
	ds_read_b128 v[132:135], v209 offset:55296
	s_waitcnt lgkmcnt(0)
	v_mfma_f32_16x16x32_bf16 v[210:213], v[132:135], v[32:35], 0
	v_mfma_f32_16x16x32_bf16 v[214:217], v[136:139], v[32:35], 0
	v_mfma_f32_16x16x32_bf16 v[210:213], v[140:143], v[36:39], v[210:213]
	v_mfma_f32_16x16x32_bf16 v[214:217], v[144:147], v[36:39], v[214:217]
	v_mfma_f32_16x16x32_bf16 v[210:213], v[148:151], v[40:43], v[210:213]
	v_mfma_f32_16x16x32_bf16 v[214:217], v[182:185], v[40:43], v[214:217]
	v_mfma_f32_16x16x32_bf16 v[210:213], v[172:175], v[44:47], v[210:213]
	v_mfma_f32_16x16x32_bf16 v[214:217], v[188:191], v[44:47], v[214:217]
	v_mfma_f32_16x16x32_bf16 v[218:221], v[132:135], v[48:51], 0
	ds_read_b128 v[132:135], v208
	s_nop 4
	v_sub_f32_e32 v222, v213, v3
	v_sub_f32_e32 v223, v212, v2
	v_sub_f32_e32 v224, v211, v1
	v_sub_f32_e32 v170, v210, v0
	v_mfma_f32_16x16x32_bf16 v[210:213], v[136:139], v[48:51], 0
	ds_read_b128 v[136:139], v208 offset:2560
	v_sub_f32_e32 v226, v217, v3
	v_sub_f32_e32 v225, v216, v2
	v_sub_f32_e32 v227, v215, v1
	v_sub_f32_e32 v228, v214, v0
	v_mfma_f32_16x16x32_bf16 v[214:217], v[140:143], v[52:55], v[218:221]
	ds_read_b128 v[140:143], v208 offset:5120
	v_exp_f32_e32 v171, v170
	v_exp_f32_e32 v225, v225
	v_mfma_f32_16x16x32_bf16 v[210:213], v[144:147], v[52:55], v[210:213]
	ds_read_b128 v[144:147], v208 offset:7680
	v_exp_f32_e32 v219, v222
	v_exp_f32_e32 v221, v228
	v_mfma_f32_16x16x32_bf16 v[214:217], v[148:151], v[56:59], v[214:217]
	ds_read_b128 v[148:151], v208 offset:10240
	v_mfma_f32_16x16x32_bf16 v[182:185], v[182:185], v[56:59], v[210:213]
	v_mfma_f32_16x16x32_bf16 v[172:175], v[172:175], v[60:63], v[214:217]
	s_nop 4
	v_exp_f32_e32 v215, v224
	v_exp_f32_e32 v217, v223
	s_nop 0
	v_sub_f32_e32 v174, v174, v2
	v_exp_f32_e32 v216, v174
	v_sub_f32_e32 v174, v175, v3
	v_sub_f32_e32 v170, v172, v0
	v_exp_f32_e32 v170, v170
	v_sub_f32_e32 v172, v173, v1
	v_exp_f32_e32 v214, v172
	v_exp_f32_e32 v218, v174
	v_add_f32_e32 v172, 0, v170
	v_add_f32_e32 v173, 0, v171
	v_exp_f32_e32 v223, v227
	v_add_f32_e32 v172, v214, v172
	v_add_f32_e32 v173, v215, v173
	v_exp_f32_e32 v227, v226
	v_add_f32_e32 v172, v216, v172
	v_add_f32_e32 v173, v217, v173
	s_nop 0
	v_add_f32_e32 v172, v218, v172
	v_add_f32_e32 v173, v219, v173
	v_mfma_f32_16x16x32_bf16 v[182:185], v[188:191], v[60:63], v[182:185]
	s_nop 7
	v_sub_f32_e32 v182, v182, v0
	v_exp_f32_e32 v220, v182
	s_nop 0
	v_add_f32_e32 v172, v220, v172
	v_add_f32_e32 v173, v221, v173
	v_sub_f32_e32 v183, v183, v1
	v_exp_f32_e32 v222, v183
	s_nop 0
	v_add_f32_e32 v172, v222, v172
	v_add_f32_e32 v173, v223, v173
	v_sub_f32_e32 v184, v184, v2
	v_exp_f32_e32 v224, v184
	s_nop 0
	v_add_f32_e32 v172, v224, v172
	v_add_f32_e32 v173, v225, v173
	v_sub_f32_e32 v185, v185, v3
	v_exp_f32_e32 v226, v185
	s_nop 0
	v_add_f32_e32 v228, v226, v172
	v_add_f32_e32 v229, v227, v173
	ds_read_b128 v[188:191], v208 offset:12800
	ds_read_b128 v[182:185], v208 offset:15360
	ds_read_b128 v[172:175], v208 offset:17920
	v_cvt_pk_bf16_f32 v210, v171, v215
	v_cvt_pk_bf16_f32 v211, v217, v219
	v_cvt_pk_bf16_f32 v212, v221, v223
	v_cvt_pk_bf16_f32 v213, v225, v227
	s_waitcnt lgkmcnt(7)
	v_mfma_f32_16x16x32_bf16 v[128:131], v[132:135], v[210:213], v[128:131]
	v_add_f32_e64 v168, v168, v228
	v_add_f32_e64 v169, v169, v229
	v_cvt_pk_bf16_f32 v214, v170, v214
	v_cvt_pk_bf16_f32 v215, v216, v218
	s_waitcnt lgkmcnt(6)
	v_mfma_f32_16x16x32_bf16 v[124:127], v[136:139], v[210:213], v[124:127]
	v_cvt_pk_bf16_f32 v216, v220, v222
	v_cvt_pk_bf16_f32 v217, v224, v226
	s_waitcnt lgkmcnt(5)
	v_mfma_f32_16x16x32_bf16 v[120:123], v[140:143], v[210:213], v[120:123]
	s_waitcnt lgkmcnt(4)
	v_mfma_f32_16x16x32_bf16 v[116:119], v[144:147], v[210:213], v[116:119]
	s_waitcnt lgkmcnt(3)
	v_mfma_f32_16x16x32_bf16 v[112:115], v[148:151], v[210:213], v[112:115]
	s_waitcnt lgkmcnt(2)
	v_mfma_f32_16x16x32_bf16 v[108:111], v[188:191], v[210:213], v[108:111]
	s_waitcnt lgkmcnt(1)
	v_mfma_f32_16x16x32_bf16 v[104:107], v[182:185], v[210:213], v[104:107]
	s_waitcnt lgkmcnt(0)
	v_mfma_f32_16x16x32_bf16 v[100:103], v[172:175], v[210:213], v[100:103]
	v_mfma_f32_16x16x32_bf16 v[96:99], v[132:135], v[214:217], v[96:99]
	v_mfma_f32_16x16x32_bf16 v[92:95], v[136:139], v[214:217], v[92:95]
	v_mfma_f32_16x16x32_bf16 v[84:87], v[140:143], v[214:217], v[84:87]
	v_mfma_f32_16x16x32_bf16 v[76:79], v[144:147], v[214:217], v[76:79]
	v_mfma_f32_16x16x32_bf16 v[72:75], v[148:151], v[214:217], v[72:75]
	v_mfma_f32_16x16x32_bf16 v[68:71], v[188:191], v[214:217], v[68:71]
	v_mfma_f32_16x16x32_bf16 v[64:67], v[182:185], v[214:217], v[64:67]
	v_mfma_f32_16x16x32_bf16 v[20:23], v[172:175], v[214:217], v[20:23]
	s_mov_b64 s[40:41], 0
	s_and_b64 vcc, exec, s[36:37]
	s_barrier
	s_cbranch_vccnz .LBB0_63
; #define LAS __attribute__((address_space(3)))
; __device__ __forceinline__ float bflo(unsigned w) { return __uint_as_float(w << 16); }
; __device__ __forceinline__ float bfhi(unsigned w) { return __uint_as_float(w & 0xffff0000u); }
; __device__ __forceinline__ unsigned pk2(float lo, float hi) { return pg8::cvt_pk_bf16(lo, hi); }
;     ...
;     auto norm16 = [&](u32x4& a, u32x4& b, const float* gn, float extra) {
;         float x[16];
; #pragma unroll
;         for (int e = 0; e < 4; ++e) { x[2 * e] = bflo(a[e]); x[2 * e + 1] = bfhi(a[e]); x[8 + 2 * e] = bflo(b[e]); x[9 + 2 * e] = bfhi(b[e]); }
;         float sq = 0.f;
; #pragma unroll
;         for (int e = 0; e < 16; ++e) sq += x[e] * x[e];
;         sq += __shfl_xor(sq, 1); sq += __shfl_xor(sq, 2); sq += __shfl_xor(sq, 4);
;         const float rs = __builtin_amdgcn_rsqf(sq * (1.f / 128.f) + EPS) * extra;
;         const f32x4 g0 = *(const f32x4*)(gn + 8 * kj), g1 = *(const f32x4*)(gn + 8 * kj + 4), g2 = *(const f32x4*)(gn + 64 + 8 * kj), g3 = *(const f32x4*)(gn + 64 + 8 * kj + 4);
;         a[0] = pk2(x[0] * rs * g0[0], x[1] * rs * g0[1]); a[1] = pk2(x[2] * rs * g0[2], x[3] * rs * g0[3]); a[2] = pk2(x[4] * rs * g1[0], x[5] * rs * g1[1]); a[3] = pk2(x[6] * rs * g1[2], x[7] * rs * g1[3]);
;         b[0] = pk2(x[8] * rs * g2[0], x[9] * rs * g2[1]); b[1] = pk2(x[10] * rs * g2[2], x[11] * rs * g2[3]); b[2] = pk2(x[12] * rs * g3[0], x[13] * rs * g3[1]); b[3] = pk2(x[14] * rs * g3[2], x[15] * rs * g3[3]);
;     };
;     ...
;     auto stage = [&](KVRegs& r, int buf) {
;         LAS bf16* Ks = (LAS bf16*)(lds + koff(buf)); LAS bf16* VT = (LAS bf16*)(lds + voff(buf));
;         if (MODE >= 1) norm16(r.ka, r.kb, kg, 1.0f);
;         *(LAS u32x4*)(Ks + kr * QP + 8 * kj) = r.ka; *(LAS u32x4*)(Ks + kr * QP + 64 + 8 * kj) = r.kb;
;         if (MODE == 0) { *(LAS u32x4*)(VT + (tid >> 2) * VPA + 16 * (tid & 3)) = r.va; *(LAS u32x4*)(VT + (tid >> 2) * VPA + 16 * (tid & 3) + 8) = r.vb; }
;         else
; #pragma unroll
;         for (int e = 0; e < 4; ++e) { const int pv = vperm(vr);
;                                       VT[(8 * vj + 2 * e) * VPA + pv] = (bf16)(r.va[e] & 0xffffu); VT[(8 * vj + 2 * e + 1) * VPA + pv] = (bf16)(r.va[e] >> 16);
;                                       VT[(64 + 8 * vj + 2 * e) * VPA + pv] = (bf16)(r.vb[e] & 0xffffu); VT[(64 + 8 * vj + 2 * e + 1) * VPA + pv] = (bf16)(r.vb[e] >> 16); } };
.LBB0_59:
	s_waitcnt vmcnt(3)
	v_and_b32_e32 v151, 0xffff0000, v12
	v_lshlrev_b32_e32 v150, 16, v12
	v_lshlrev_b32_e32 v182, 16, v14
	v_and_b32_e32 v149, 0xffff0000, v14
	v_mul_f32_e32 v14, v151, v151
	v_lshlrev_b32_e32 v174, 16, v13
	v_fmac_f32_e32 v14, v150, v150
	v_and_b32_e32 v175, 0xffff0000, v13
	v_fmac_f32_e32 v14, v174, v174
	v_fmac_f32_e32 v14, v175, v175
	v_fmac_f32_e32 v14, v182, v182
	v_lshlrev_b32_e32 v148, 16, v15
	v_fmac_f32_e32 v14, v149, v149
	v_and_b32_e32 v147, 0xffff0000, v15
	v_fmac_f32_e32 v14, v148, v148
	s_waitcnt vmcnt(2)
	v_lshlrev_b32_e32 v146, 16, v16
	v_fmac_f32_e32 v14, v147, v147
	v_and_b32_e32 v145, 0xffff0000, v16
	v_fmac_f32_e32 v14, v146, v146
	v_lshlrev_b32_e32 v144, 16, v17
	v_fmac_f32_e32 v14, v145, v145
	v_and_b32_e32 v143, 0xffff0000, v17
	v_fmac_f32_e32 v14, v144, v144
	v_lshlrev_b32_e32 v142, 16, v18
	v_fmac_f32_e32 v14, v143, v143
	v_and_b32_e32 v18, 0xffff0000, v18
	v_fmac_f32_e32 v14, v142, v142
	v_and_b32_e32 v140, 0xffff0000, v19
	v_lshlrev_b32_e32 v141, 16, v19
	v_fmac_f32_e32 v14, v18, v18
	v_mul_f32_e32 v12, v140, v140
	v_mul_f32_e32 v13, v141, v141
	s_xor_b64 s[36:37], s[40:41], -1
	v_add_f32_e32 v13, v13, v14
	global_load_dwordx4 v[14:17], v[158:159], off offset:16
	global_load_dwordx4 v[170:173], v[158:159], off
	global_load_dwordx4 v[132:135], v[158:159], off offset:272
	global_load_dwordx4 v[136:139], v[158:159], off offset:256
	v_add_f32_e32 v12, v12, v13
	ds_bpermute_b32 v13, v155, v12
	s_and_b64 vcc, exec, s[36:37]
	s_waitcnt lgkmcnt(0)
	v_add_f32_e32 v12, v12, v13
	ds_bpermute_b32 v13, v157, v12
	s_waitcnt lgkmcnt(0)
	v_add_f32_e32 v12, v12, v13
	ds_bpermute_b32 v13, v192, v12
	s_waitcnt lgkmcnt(0)
	v_add_f32_e32 v12, v12, v13
	v_fmamk_f32 v12, v12, 0x3c000000, v177
	v_rsq_f32_e32 v19, v12
	s_nop 0
	v_mul_f32_e32 v12, v19, v150
	v_mul_f32_e32 v13, v19, v151
	v_mul_f32_e32 v150, v19, v175
	v_mul_f32_e32 v149, v19, v149
	v_mul_f32_e32 v18, v19, v18
	s_waitcnt vmcnt(3)
	v_mul_f32_e32 v15, v15, v149
	s_waitcnt vmcnt(2)
	v_mul_f32_e32 v12, v170, v12
	v_mul_f32_e32 v13, v171, v13
	v_cvt_pk_bf16_f32 v12, v12, v13
	v_mul_f32_e32 v13, v19, v174
	v_mul_f32_e32 v13, v172, v13
	v_mul_f32_e32 v150, v173, v150
	v_cvt_pk_bf16_f32 v13, v13, v150
	v_mul_f32_e32 v150, v19, v182
	v_mul_f32_e32 v14, v14, v150
	v_cvt_pk_bf16_f32 v14, v14, v15
	v_mul_f32_e32 v15, v19, v148
	v_mul_f32_e32 v15, v16, v15
	v_mul_f32_e32 v16, v19, v147
	v_mul_f32_e32 v16, v17, v16
	v_cvt_pk_bf16_f32 v15, v15, v16
	v_mul_f32_e32 v16, v19, v146
	v_mul_f32_e32 v17, v19, v145
	s_waitcnt vmcnt(0)
	v_mul_f32_e32 v16, v136, v16
	v_mul_f32_e32 v17, v137, v17
	v_cvt_pk_bf16_f32 v16, v16, v17
	v_mul_f32_e32 v17, v19, v144
	v_mul_f32_e32 v136, v19, v143
	v_mul_f32_e32 v17, v138, v17
	v_mul_f32_e32 v136, v139, v136
	v_cvt_pk_bf16_f32 v17, v17, v136
	v_mul_f32_e32 v136, v19, v142
	v_mul_f32_e32 v132, v132, v136
	v_mul_f32_e32 v18, v133, v18
	v_cvt_pk_bf16_f32 v18, v132, v18
	v_mul_f32_e32 v132, v19, v141
	v_mul_f32_e32 v19, v19, v140
	v_mul_f32_e32 v19, v135, v19
	v_mul_f32_e32 v132, v134, v132
	v_cvt_pk_bf16_f32 v19, v132, v19
	ds_write_b128 v195, v[12:15] offset:55296
	ds_write_b128 v195, v[16:19] offset:55424
	ds_write_b16 v198, v4
	ds_write_b16_d16_hi v198, v4 offset:160
	ds_write_b16 v198, v8 offset:10240
	ds_write_b16_d16_hi v198, v8 offset:10400
	ds_write_b16 v198, v5 offset:320
	ds_write_b16_d16_hi v198, v5 offset:480
	ds_write_b16 v198, v9 offset:10560
	ds_write_b16_d16_hi v198, v9 offset:10720
	ds_write_b16 v198, v6 offset:640
	ds_write_b16_d16_hi v198, v6 offset:800
	ds_write_b16 v198, v10 offset:10880
	ds_write_b16_d16_hi v198, v10 offset:11040
	ds_write_b16 v198, v7 offset:960
	ds_write_b16_d16_hi v198, v7 offset:1120
	ds_write_b16 v198, v11 offset:11200
	ds_write_b16_d16_hi v198, v11 offset:11360
	s_cbranch_vccnz .LBB0_61
	global_load_dwordx4 v[12:15], v[162:163], off
	global_load_dwordx4 v[16:19], v[162:163], off offset:128
	global_load_dwordx4 v[4:7], v[164:165], off
	global_load_dwordx4 v[8:11], v[166:167], off
.LBB0_61:
	ds_read_b128 v[140:143], v209 offset:36992
	ds_read_b128 v[144:147], v209 offset:37056
	ds_read_b128 v[148:151], v209 offset:41472
	ds_read_b128 v[170:173], v209 offset:41536
	ds_read_b128 v[132:135], v209 offset:36864
	ds_read_b128 v[136:139], v209 offset:36928
	ds_read_b128 v[182:185], v209 offset:41600
	ds_read_b128 v[188:191], v209 offset:41664
	s_waitcnt lgkmcnt(3)
	v_mfma_f32_16x16x32_bf16 v[210:213], v[132:135], v[32:35], 0
	v_mfma_f32_16x16x32_bf16 v[214:217], v[148:151], v[32:35], 0
	s_waitcnt lgkmcnt(2)
	v_mfma_f32_16x16x32_bf16 v[210:213], v[136:139], v[36:39], v[210:213]
	v_mfma_f32_16x16x32_bf16 v[214:217], v[170:173], v[36:39], v[214:217]
	v_mfma_f32_16x16x32_bf16 v[210:213], v[140:143], v[40:43], v[210:213]
	s_waitcnt lgkmcnt(1)
	v_mfma_f32_16x16x32_bf16 v[214:217], v[182:185], v[40:43], v[214:217]
	v_mfma_f32_16x16x32_bf16 v[210:213], v[144:147], v[44:47], v[210:213]
	s_waitcnt lgkmcnt(0)
; #define LAS __attribute__((address_space(3)))
; #define MMA16(X, Y, ACC) ACC = __builtin_amdgcn_mfma_f32_16x16x32_bf16((X), (Y), (ACC), 0, 0, 0)
;     ...
; #pragma unroll
;         for (int ks = 0; ks < 4; ++ks)
; #pragma unroll
;             for (int kb = 0; kb < 2; ++kb) MMA16(kf[kb][ks], qf[0][ks], s[0][kb]);
;         __builtin_amdgcn_sched_barrier(0);
;         bf16x8 vf[8];
; #pragma unroll
;         for (int db = 0; db < 8; ++db) vf[db] = *(const LAS bf16x8*)(VT + (16 * db + fr) * VPA + 32 * kh + 8 * fq);
;         if (MODE == 0) { const LAS float* bp = BT + (2047 - 16 - (q0 + 32 * rp + fr - t * 64 - 32 * kh - 4 * fq));
; #pragma unroll
;             for (int kb = 0; kb < 2; ++kb)
; #pragma unroll
;                 for (int i = 0; i < 4; ++i) bias[1][kb][i] = bp[16 * kb + i]; }
; #pragma unroll
;         for (int ks = 0; ks < 4; ++ks)
; #pragma unroll
;             for (int kb = 0; kb < 2; ++kb) MMA16(kf[kb][ks], qf[1][ks], s[1][kb]);
;         smax(0);
; #pragma unroll
;         for (int g = 0; g < 8; ++g) { __builtin_amdgcn_sched_group_barrier(0x008, 1, 0); __builtin_amdgcn_sched_group_barrier(0x100, 1, 0); __builtin_amdgcn_sched_group_barrier(0x002, 4, 0); }
;         __builtin_amdgcn_sched_barrier(0);
; #pragma unroll
;         for (int db = 0; db < 8; ++db) MMA16(vf[db], pf[0], o[0][db]);
;         smax(1);
; #pragma unroll
;         for (int g = 0; g < 8; ++g) { __builtin_amdgcn_sched_group_barrier(0x008, 1, 1); __builtin_amdgcn_sched_group_barrier(0x002, 4, 1); }
;         __builtin_amdgcn_sched_barrier(0);
; #pragma unroll
;         for (int db = 0; db < 8; ++db) MMA16(vf[db], pf[1], o[1][db]);
;         __builtin_amdgcn_sched_barrier(0);
	v_mfma_f32_16x16x32_bf16 v[214:217], v[188:191], v[44:47], v[214:217]
	v_mfma_f32_16x16x32_bf16 v[132:135], v[132:135], v[48:51], 0
	ds_read_b128 v[218:221], v207
	s_nop 3
	v_sub_f32_e32 v174, v213, v3
	v_sub_f32_e32 v175, v212, v2
	v_sub_f32_e32 v230, v211, v1
	v_sub_f32_e32 v231, v210, v0
	v_mfma_f32_16x16x32_bf16 v[148:151], v[148:151], v[48:51], 0
	ds_read_b128 v[210:213], v207 offset:2560
	v_sub_f32_e32 v232, v217, v3
	v_sub_f32_e32 v233, v216, v2
	v_sub_f32_e32 v234, v215, v1
	v_sub_f32_e32 v235, v214, v0
	v_mfma_f32_16x16x32_bf16 v[132:135], v[136:139], v[52:55], v[132:135]
	ds_read_b128 v[136:139], v207 offset:5120
	v_mfma_f32_16x16x32_bf16 v[148:151], v[170:173], v[52:55], v[148:151]
	ds_read_b128 v[214:217], v207 offset:7680
	v_exp_f32_e32 v173, v231
	v_exp_f32_e32 v171, v230
	v_mfma_f32_16x16x32_bf16 v[132:135], v[140:143], v[56:59], v[132:135]
	ds_read_b128 v[222:225], v207 offset:10240
	v_mfma_f32_16x16x32_bf16 v[140:143], v[182:185], v[56:59], v[148:151]
	ds_read_b128 v[182:185], v207 offset:12800
	v_mfma_f32_16x16x32_bf16 v[132:135], v[144:147], v[60:63], v[132:135]
	ds_read_b128 v[226:229], v207 offset:15360
	v_exp_f32_e32 v151, v175
	v_exp_f32_e32 v149, v174
	v_exp_f32_e32 v147, v235
	v_exp_f32_e32 v145, v234
	s_nop 2
	v_sub_f32_e32 v144, v135, v3
	v_sub_f32_e32 v146, v134, v2
	v_sub_f32_e32 v148, v133, v1
	v_sub_f32_e32 v150, v132, v0
	v_mfma_f32_16x16x32_bf16 v[132:135], v[188:191], v[60:63], v[140:143]
	ds_read_b128 v[188:191], v207 offset:17920
	v_exp_f32_e32 v172, v150
	v_exp_f32_e32 v170, v148
	v_exp_f32_e32 v143, v233
	v_exp_f32_e32 v141, v232
	s_nop 2
	v_sub_f32_e32 v135, v135, v3
	v_sub_f32_e32 v134, v134, v2
	v_sub_f32_e32 v133, v133, v1
	v_sub_f32_e32 v132, v132, v0
	v_exp_f32_e32 v150, v146
	v_exp_f32_e32 v148, v144
	v_exp_f32_e32 v146, v132
	v_exp_f32_e32 v144, v133
	v_exp_f32_e32 v142, v134
	v_exp_f32_e32 v140, v135
	v_cvt_pk_bf16_f32 v132, v173, v171
	v_cvt_pk_bf16_f32 v133, v151, v149
	v_cvt_pk_bf16_f32 v134, v147, v145
	v_cvt_pk_bf16_f32 v135, v143, v141
	s_waitcnt lgkmcnt(7)
	v_mfma_f32_16x16x32_bf16 v[128:131], v[218:221], v[132:135], v[128:131]
	s_waitcnt lgkmcnt(6)
	v_mfma_f32_16x16x32_bf16 v[124:127], v[210:213], v[132:135], v[124:127]
	s_waitcnt lgkmcnt(5)
	v_mfma_f32_16x16x32_bf16 v[120:123], v[136:139], v[132:135], v[120:123]
	s_waitcnt lgkmcnt(4)
	v_mfma_f32_16x16x32_bf16 v[116:119], v[214:217], v[132:135], v[116:119]
	s_waitcnt lgkmcnt(3)
	v_mfma_f32_16x16x32_bf16 v[112:115], v[222:225], v[132:135], v[112:115]
	s_waitcnt lgkmcnt(2)
	v_mfma_f32_16x16x32_bf16 v[108:111], v[182:185], v[132:135], v[108:111]
	s_waitcnt lgkmcnt(1)
	v_mfma_f32_16x16x32_bf16 v[104:107], v[226:229], v[132:135], v[104:107]
	s_waitcnt lgkmcnt(0)
	v_mfma_f32_16x16x32_bf16 v[100:103], v[188:191], v[132:135], v[100:103]
	v_cvt_pk_bf16_f32 v132, v172, v170
	v_cvt_pk_bf16_f32 v133, v150, v148
	v_cvt_pk_bf16_f32 v134, v146, v144
	v_cvt_pk_bf16_f32 v135, v142, v140
	s_nop 0
	v_mfma_f32_16x16x32_bf16 v[96:99], v[218:221], v[132:135], v[96:99]
	v_mfma_f32_16x16x32_bf16 v[92:95], v[210:213], v[132:135], v[92:95]
	v_mfma_f32_16x16x32_bf16 v[84:87], v[136:139], v[132:135], v[84:87]
	v_mfma_f32_16x16x32_bf16 v[76:79], v[214:217], v[132:135], v[76:79]
	v_mfma_f32_16x16x32_bf16 v[72:75], v[222:225], v[132:135], v[72:75]
	v_mfma_f32_16x16x32_bf16 v[68:71], v[182:185], v[132:135], v[68:71]
	v_mfma_f32_16x16x32_bf16 v[64:67], v[226:229], v[132:135], v[64:67]
	v_mfma_f32_16x16x32_bf16 v[20:23], v[188:191], v[132:135], v[20:23]
	s_andn2_b64 vcc, exec, s[40:41]
	s_barrier
	s_cbranch_vccnz .LBB0_58
; #define LAS __attribute__((address_space(3)))
; __device__ __forceinline__ float bflo(unsigned w) { return __uint_as_float(w << 16); }
; __device__ __forceinline__ float bfhi(unsigned w) { return __uint_as_float(w & 0xffff0000u); }
; __device__ __forceinline__ unsigned pk2(float lo, float hi) { return pg8::cvt_pk_bf16(lo, hi); }
;     ...
;     auto norm16 = [&](u32x4& a, u32x4& b, const float* gn, float extra) {
;         float x[16];
; #pragma unroll
;         for (int e = 0; e < 4; ++e) { x[2 * e] = bflo(a[e]); x[2 * e + 1] = bfhi(a[e]); x[8 + 2 * e] = bflo(b[e]); x[9 + 2 * e] = bfhi(b[e]); }
;         float sq = 0.f;
; #pragma unroll
;         for (int e = 0; e < 16; ++e) sq += x[e] * x[e];
;         sq += __shfl_xor(sq, 1); sq += __shfl_xor(sq, 2); sq += __shfl_xor(sq, 4);
;         const float rs = __builtin_amdgcn_rsqf(sq * (1.f / 128.f) + EPS) * extra;
;         const f32x4 g0 = *(const f32x4*)(gn + 8 * kj), g1 = *(const f32x4*)(gn + 8 * kj + 4), g2 = *(const f32x4*)(gn + 64 + 8 * kj), g3 = *(const f32x4*)(gn + 64 + 8 * kj + 4);
;         a[0] = pk2(x[0] * rs * g0[0], x[1] * rs * g0[1]); a[1] = pk2(x[2] * rs * g0[2], x[3] * rs * g0[3]); a[2] = pk2(x[4] * rs * g1[0], x[5] * rs * g1[1]); a[3] = pk2(x[6] * rs * g1[2], x[7] * rs * g1[3]);
;         b[0] = pk2(x[8] * rs * g2[0], x[9] * rs * g2[1]); b[1] = pk2(x[10] * rs * g2[2], x[11] * rs * g2[3]); b[2] = pk2(x[12] * rs * g3[0], x[13] * rs * g3[1]); b[3] = pk2(x[14] * rs * g3[2], x[15] * rs * g3[3]);
;     };
;     ...
;     auto stage = [&](KVRegs& r, int buf) {
;         LAS bf16* Ks = (LAS bf16*)(lds + koff(buf)); LAS bf16* VT = (LAS bf16*)(lds + voff(buf));
;         if (MODE >= 1) norm16(r.ka, r.kb, kg, 1.0f);
;         *(LAS u32x4*)(Ks + kr * QP + 8 * kj) = r.ka; *(LAS u32x4*)(Ks + kr * QP + 64 + 8 * kj) = r.kb;
;         if (MODE == 0) { *(LAS u32x4*)(VT + (tid >> 2) * VPA + 16 * (tid & 3)) = r.va; *(LAS u32x4*)(VT + (tid >> 2) * VPA + 16 * (tid & 3) + 8) = r.vb; }
;         else
; #pragma unroll
;         for (int e = 0; e < 4; ++e) { const int pv = vperm(vr);
;                                       VT[(8 * vj + 2 * e) * VPA + pv] = (bf16)(r.va[e] & 0xffffu); VT[(8 * vj + 2 * e + 1) * VPA + pv] = (bf16)(r.va[e] >> 16);
;                                       VT[(64 + 8 * vj + 2 * e) * VPA + pv] = (bf16)(r.vb[e] & 0xffffu); VT[(64 + 8 * vj + 2 * e + 1) * VPA + pv] = (bf16)(r.vb[e] >> 16); } };
	v_and_b32_e32 v183, 0xffff0000, v80
	v_lshlrev_b32_e32 v182, 16, v80
	v_lshlrev_b32_e32 v211, 16, v82
	v_and_b32_e32 v212, 0xffff0000, v82
	v_mul_f32_e32 v82, v183, v183
	v_lshlrev_b32_e32 v188, 16, v81
	v_fmac_f32_e32 v82, v182, v182
	v_and_b32_e32 v189, 0xffff0000, v81
	v_fmac_f32_e32 v82, v188, v188
	v_fmac_f32_e32 v82, v189, v189
	v_fmac_f32_e32 v82, v211, v211
	v_lshlrev_b32_e32 v215, 16, v83
	v_fmac_f32_e32 v82, v212, v212
	v_and_b32_e32 v216, 0xffff0000, v83
	v_fmac_f32_e32 v82, v215, v215
	v_lshlrev_b32_e32 v184, 16, v88
	v_fmac_f32_e32 v82, v216, v216
	v_and_b32_e32 v185, 0xffff0000, v88
	v_fmac_f32_e32 v82, v184, v184
	v_lshlrev_b32_e32 v190, 16, v89
	v_fmac_f32_e32 v82, v185, v185
	v_and_b32_e32 v191, 0xffff0000, v89
	v_fmac_f32_e32 v82, v190, v190
	v_lshlrev_b32_e32 v213, 16, v90
	v_fmac_f32_e32 v82, v191, v191
	v_and_b32_e32 v214, 0xffff0000, v90
	v_fmac_f32_e32 v82, v213, v213
	v_and_b32_e32 v174, 0xffff0000, v91
	v_lshlrev_b32_e32 v175, 16, v91
	v_fmac_f32_e32 v82, v214, v214
	v_mul_f32_e32 v80, v174, v174
	v_mul_f32_e32 v81, v175, v175
	s_nop 0
	v_add_f32_e32 v81, v81, v82
	v_add_f32_e32 v80, v80, v81
	ds_bpermute_b32 v81, v155, v80
	s_waitcnt lgkmcnt(0)
	v_add_f32_e32 v80, v80, v81
	ds_bpermute_b32 v81, v157, v80
	s_waitcnt lgkmcnt(0)
	v_add_f32_e32 v80, v80, v81
	ds_bpermute_b32 v81, v192, v80
	s_waitcnt lgkmcnt(0)
	v_add_f32_e32 v80, v80, v81
	v_fmamk_f32 v80, v80, 0x3c000000, v177
	v_rsq_f32_e32 v210, v80
	global_load_dwordx4 v[88:91], v[158:159], off offset:16
	global_load_dwordx4 v[80:83], v[158:159], off
	global_load_dwordx4 v[132:135], v[158:159], off offset:272
	global_load_dwordx4 v[136:139], v[158:159], off offset:256
	v_mul_f32_e32 v182, v210, v182
	s_waitcnt vmcnt(2)
	v_mul_f32_e32 v80, v80, v182
	v_mul_f32_e32 v182, v210, v183
	v_mul_f32_e32 v81, v81, v182
	v_cvt_pk_bf16_f32 v80, v80, v81
	v_mul_f32_e32 v81, v210, v188
	v_mul_f32_e32 v81, v82, v81
	v_mul_f32_e32 v82, v210, v189
	v_mul_f32_e32 v82, v83, v82
	v_cvt_pk_bf16_f32 v81, v81, v82
	v_mul_f32_e32 v82, v210, v211
	v_mul_f32_e32 v83, v210, v212
	v_mul_f32_e32 v82, v88, v82
	v_mul_f32_e32 v83, v89, v83
	v_cvt_pk_bf16_f32 v82, v82, v83
	v_mul_f32_e32 v83, v210, v215
	v_mul_f32_e32 v88, v210, v216
	v_mul_f32_e32 v83, v90, v83
	v_mul_f32_e32 v88, v91, v88
	v_cvt_pk_bf16_f32 v83, v83, v88
	v_mul_f32_e32 v88, v210, v184
	v_mul_f32_e32 v89, v210, v185
	s_waitcnt vmcnt(0)
	v_mul_f32_e32 v88, v136, v88
	v_mul_f32_e32 v89, v137, v89
	v_cvt_pk_bf16_f32 v88, v88, v89
	v_mul_f32_e32 v89, v210, v190
	v_mul_f32_e32 v90, v210, v191
	v_mul_f32_e32 v89, v138, v89
	v_mul_f32_e32 v90, v139, v90
	v_cvt_pk_bf16_f32 v89, v89, v90
	v_mul_f32_e32 v90, v210, v213
	v_mul_f32_e32 v91, v210, v214
	v_mul_f32_e32 v90, v132, v90
	v_mul_f32_e32 v91, v133, v91
	v_cvt_pk_bf16_f32 v90, v90, v91
	v_mul_f32_e32 v91, v210, v175
	v_mul_f32_e32 v91, v134, v91
	v_mul_f32_e32 v132, v210, v174
	v_mul_f32_e32 v132, v135, v132
	v_cvt_pk_bf16_f32 v91, v91, v132
	ds_write_b128 v195, v[80:83] offset:36864
	ds_write_b128 v195, v[88:91] offset:36992
	ds_write_b16 v196, v24
	ds_write_b16 v196, v199 offset:160
	ds_write_b16 v196, v28 offset:10240
	ds_write_b16 v196, v200 offset:10400
	ds_write_b16 v196, v25 offset:320
	ds_write_b16 v196, v201 offset:480
	ds_write_b16 v196, v29 offset:10560
	ds_write_b16 v196, v202 offset:10720
	ds_write_b16 v196, v26 offset:640
	ds_write_b16 v196, v203 offset:800
	ds_write_b16 v196, v30 offset:10880
	ds_write_b16 v196, v204 offset:11040
	ds_write_b16 v196, v27 offset:960
	ds_write_b16 v196, v205 offset:1120
	ds_write_b16 v196, v31 offset:11200
	ds_write_b16 v196, v206 offset:11360
	s_branch .LBB0_58

;     ...
;     auto compute = [&](int buf, int t) {
;         const LAS bf16* Ks = (const LAS bf16*)(lds + koff(buf)); const LAS bf16* VT = (const LAS bf16*)(lds + voff(buf));
;         bf16x8 kf[2][4]; float bias[2][2][4];
; #pragma unroll
;         for (int kb = 0; kb < 2; ++kb)
; #pragma unroll
;             for (int ks = 0; ks < 4; ++ks) kf[kb][ks] = *(const LAS bf16x8*)(Ks + (32 * kh + 16 * kb + fr) * QP + 32 * ks + 8 * fq);
;         if (MODE == 0) { const LAS float* bp = BT + (2047 - 16 - (q0 + 32 * rp + fr - t * 64 - 32 * kh - 4 * fq));
; #pragma unroll
;                 for (int kb = 0; kb < 2; ++kb)
; #pragma unroll
;                     for (int i = 0; i < 4; ++i) bias[0][kb][i] = bp[16 * (kb + 1) + i]; }
;         __builtin_amdgcn_sched_barrier(0);
;         f32x4 s[2][2];
; #pragma unroll
;         for (int rb = 0; rb < 2; ++rb)
; #pragma unroll
;             for (int kb = 0; kb < 2; ++kb) s[rb][kb] = (f32x4){0.f, 0.f, 0.f, 0.f};
;         bf16x8 pf[2];
;         auto smax = [&](int rb) {
;             if (MODE == 0) { s[rb][0] = s[rb][0] + (f32x4){bias[rb][0][0], bias[rb][0][1], bias[rb][0][2], bias[rb][0][3]}; s[rb][1] = s[rb][1] + (f32x4){bias[rb][1][0], bias[rb][1][1], bias[rb][1][2], bias[rb][1][3]}; }
;             else { s[rb][0] = s[rb][0] - bref; s[rb][1] = s[rb][1] - bref; }
;             float ps = 0.f;
; #pragma unroll
;             for (int kb = 0; kb < 2; ++kb)
; #pragma unroll
;                 for (int i = 0; i < 4; ++i) { s[rb][kb][i] = __builtin_amdgcn_exp2f(s[rb][kb][i]); ps += s[rb][kb][i]; }
;             lrun[rb] += ps;
;             u32x4 pw; pw.x = pk2(s[rb][0][0], s[rb][0][1]); pw.y = pk2(s[rb][0][2], s[rb][0][3]); pw.z = pk2(s[rb][1][0], s[rb][1][1]); pw.w = pk2(s[rb][1][2], s[rb][1][3]);
;             pf[rb] = __builtin_bit_cast(bf16x8, pw); };
; #pragma unroll
;         for (int ks = 0; ks < 4; ++ks)
; #pragma unroll
;             for (int kb = 0; kb < 2; ++kb) MMA16(kf[kb][ks], qf[0][ks], s[0][kb]);
;         __builtin_amdgcn_sched_barrier(0);
;         bf16x8 vf[8];
; #pragma unroll
;         for (int db = 0; db < 8; ++db) vf[db] = *(const LAS bf16x8*)(VT + (16 * db + fr) * VPA + 32 * kh + 8 * fq);
;         if (MODE == 0) { const LAS float* bp = BT + (2047 - 16 - (q0 + 32 * rp + fr - t * 64 - 32 * kh - 4 * fq));
; #pragma unroll
;             for (int kb = 0; kb < 2; ++kb)
; #pragma unroll
.LBB0_121:
	v_add_f32_e32 v142, 0, v142
	v_add_f32_e32 v143, 0, v143
	s_add_i32 s78, s78, 0x9800
	v_add_f32_e32 v140, v140, v142
	v_add_f32_e32 v141, v141, v143
	s_cmp_lt_i32 s63, 2
	v_add_f32_e32 v138, v138, v140
	v_add_f32_e32 v139, v139, v141
	s_cselect_b32 s63, s78, 0
	v_add_f32_e32 v136, v136, v138
	v_add_f32_e32 v137, v137, v139
	s_add_i32 s63, s63, 0
	v_add_f32_e32 v134, v134, v136
	v_add_f32_e32 v135, v135, v137
	v_add_u32_e32 v171, s63, v165
	v_add_f32_e32 v132, v132, v134
	v_add_f32_e32 v133, v133, v135
	v_add_u32_e32 v182, v171, v167
	v_add_f32_e32 v130, v130, v132
	v_add_f32_e32 v131, v131, v133
	ds_read_b128 v[132:135], v182 offset:64
	v_add_f32_e32 v128, v128, v130
	v_add_f32_e32 v129, v129, v131
	ds_read_b128 v[140:143], v182 offset:128
	v_add_f32_e32 v150, v150, v128
	v_add_f32_e32 v151, v151, v129
	ds_read_b128 v[128:131], v182
	ds_read_b128 v[172:175], v182 offset:192
	ds_read_b128 v[136:139], v182 offset:4608
	ds_read_b128 v[144:147], v182 offset:4672
	ds_read_b128 v[192:195], v182 offset:4736
	ds_read_b128 v[196:199], v182 offset:4800
	ds_read2_b32 v[182:183], v170 offset0:80 offset1:81
	ds_read2_b32 v[184:185], v170 offset0:82 offset1:83
	ds_read2_b32 v[188:189], v170 offset0:96 offset1:97
	ds_read2_b32 v[190:191], v170 offset0:98 offset1:99
	s_waitcnt lgkmcnt(9)
	v_mfma_f32_16x16x32_bf16 v[200:203], v[128:131], v[76:79], 0
	s_waitcnt lgkmcnt(7)
	v_mfma_f32_16x16x32_bf16 v[204:207], v[136:139], v[76:79], 0
	v_mfma_f32_16x16x32_bf16 v[200:203], v[132:135], v[80:83], v[200:203]
	s_waitcnt lgkmcnt(6)
	v_mfma_f32_16x16x32_bf16 v[204:207], v[144:147], v[80:83], v[204:207]
	v_mfma_f32_16x16x32_bf16 v[200:203], v[140:143], v[84:87], v[200:203]
	s_waitcnt lgkmcnt(5)
	v_mfma_f32_16x16x32_bf16 v[204:207], v[192:195], v[84:87], v[204:207]
	v_mfma_f32_16x16x32_bf16 v[200:203], v[172:175], v[88:91], v[200:203]
	s_waitcnt lgkmcnt(4)
	v_mfma_f32_16x16x32_bf16 v[204:207], v[196:199], v[88:91], v[204:207]
	v_mfma_f32_16x16x32_bf16 v[208:211], v[128:131], v[92:95], 0
	ds_read2_b32 v[212:213], v170 offset0:64 offset1:65
	v_add3_u32 v171, v171, v168, v169
	s_waitcnt lgkmcnt(3)
	s_nop 1
	v_add_f32_e32 v184, v184, v202
	v_add_f32_e32 v185, v185, v203
	v_add_f32_e32 v182, v182, v200
	v_add_f32_e32 v183, v183, v201
	s_waitcnt lgkmcnt(1)
	v_add_f32_e32 v190, v190, v206
	v_add_f32_e32 v191, v191, v207
	v_mfma_f32_16x16x32_bf16 v[136:139], v[136:139], v[92:95], 0
	ds_read_b128 v[128:131], v171 offset:36352
	v_add_f32_e32 v188, v188, v204
	v_add_f32_e32 v189, v189, v205
	v_exp_f32_e32 v207, v182
	v_mfma_f32_16x16x32_bf16 v[200:203], v[132:135], v[96:99], v[208:211]
	ds_read_b128 v[132:135], v171 offset:18432
	v_exp_f32_e32 v183, v183
	v_exp_f32_e32 v185, v185
	v_mfma_f32_16x16x32_bf16 v[144:147], v[144:147], v[96:99], v[136:139]
	v_exp_f32_e32 v209, v184
	v_exp_f32_e32 v211, v188
	v_exp_f32_e32 v189, v189
	ds_read_b128 v[136:139], v171 offset:20992
	v_mfma_f32_16x16x32_bf16 v[200:203], v[140:143], v[100:103], v[200:203]
	ds_read_b128 v[140:143], v171 offset:23552
	v_exp_f32_e32 v191, v191
	v_mfma_f32_16x16x32_bf16 v[192:195], v[192:195], v[100:103], v[144:147]
	s_nop 2
	ds_read_b128 v[144:147], v171 offset:26112
	v_mfma_f32_16x16x32_bf16 v[192:195], v[196:199], v[104:107], v[192:195]
	v_mfma_f32_16x16x32_bf16 v[172:175], v[172:175], v[104:107], v[200:203]
	ds_read2_b32 v[196:197], v170 offset0:66 offset1:67
	s_waitcnt lgkmcnt(0)
	s_nop 5
	v_add_f32_e32 v174, v196, v174
	v_add_f32_e32 v175, v197, v175
	ds_read_b128 v[196:199], v171 offset:33792
	v_exp_f32_e32 v208, v174
	v_exp_f32_e32 v184, v175
	ds_read2_b32 v[174:175], v170 offset0:82 offset1:83
	s_waitcnt lgkmcnt(0)
	v_add_f32_e32 v174, v174, v194
	v_add_f32_e32 v175, v175, v195
	ds_read2_b32 v[204:205], v170 offset0:80 offset1:81
	s_waitcnt lgkmcnt(0)
	v_add_f32_e32 v192, v204, v192
	v_add_f32_e32 v193, v205, v193
	v_add_f32_e32 v172, v212, v172
	v_add_f32_e32 v173, v213, v173
	v_exp_f32_e32 v210, v192
	v_exp_f32_e32 v206, v172
	v_exp_f32_e32 v182, v173
	v_exp_f32_e32 v188, v193
	v_exp_f32_e32 v213, v190
	v_add_f32_e32 v172, 0, v206
	v_add_f32_e32 v173, 0, v207
	v_exp_f32_e32 v212, v174
	v_add_f32_e32 v172, v182, v172
	v_add_f32_e32 v173, v183, v173
	v_exp_f32_e32 v190, v175
	v_add_f32_e32 v172, v208, v172
	v_add_f32_e32 v173, v209, v173
	ds_read_b128 v[192:195], v171 offset:31232
	v_add_f32_e32 v172, v184, v172
	v_add_f32_e32 v173, v185, v173
	s_nop 0
	v_add_f32_e32 v172, v210, v172
	v_add_f32_e32 v173, v211, v173
	s_nop 0
	v_add_f32_e32 v172, v188, v172
	v_add_f32_e32 v173, v189, v173
	s_nop 0
	v_add_f32_e32 v172, v212, v172
	v_add_f32_e32 v173, v213, v173
	s_nop 0
	v_add_f32_e32 v204, v190, v172
	v_add_f32_e32 v205, v191, v173
	ds_read_b128 v[172:175], v171 offset:28672
	v_cvt_pk_bf16_f32 v200, v207, v183
	v_cvt_pk_bf16_f32 v201, v209, v185
	v_cvt_pk_bf16_f32 v202, v211, v189
	v_cvt_pk_bf16_f32 v203, v213, v191
	s_nop 0
	v_mfma_f32_16x16x32_bf16 v[124:127], v[132:135], v[200:203], v[124:127]
	v_add_f32_e64 v150, v150, v204
	v_add_f32_e64 v151, v151, v205
	v_cvt_pk_bf16_f32 v204, v206, v182
	v_cvt_pk_bf16_f32 v205, v208, v184
	v_mfma_f32_16x16x32_bf16 v[120:123], v[136:139], v[200:203], v[120:123]
	v_cvt_pk_bf16_f32 v206, v210, v188
	v_cvt_pk_bf16_f32 v207, v212, v190
	v_mfma_f32_16x16x32_bf16 v[116:119], v[140:143], v[200:203], v[116:119]
	v_mfma_f32_16x16x32_bf16 v[112:115], v[144:147], v[200:203], v[112:115]
	s_waitcnt lgkmcnt(0)
	v_mfma_f32_16x16x32_bf16 v[108:111], v[172:175], v[200:203], v[108:111]
	v_mfma_f32_16x16x32_bf16 v[72:75], v[192:195], v[200:203], v[72:75]
	v_mfma_f32_16x16x32_bf16 v[68:71], v[196:199], v[200:203], v[68:71]
	v_mfma_f32_16x16x32_bf16 v[64:67], v[128:131], v[200:203], v[64:67]
	v_mfma_f32_16x16x32_bf16 v[28:31], v[132:135], v[204:207], v[28:31]
	v_mfma_f32_16x16x32_bf16 v[24:27], v[136:139], v[204:207], v[24:27]
	v_mfma_f32_16x16x32_bf16 v[20:23], v[140:143], v[204:207], v[20:23]
	v_mfma_f32_16x16x32_bf16 v[16:19], v[144:147], v[204:207], v[16:19]
	v_mfma_f32_16x16x32_bf16 v[12:15], v[172:175], v[204:207], v[12:15]
	v_mfma_f32_16x16x32_bf16 v[8:11], v[192:195], v[204:207], v[8:11]
	v_mfma_f32_16x16x32_bf16 v[4:7], v[196:199], v[204:207], v[4:7]
	v_mfma_f32_16x16x32_bf16 v[0:3], v[128:131], v[204:207], v[0:3]
	s_mov_b64 s[68:69], 0x100
	v_lshl_add_u64 v[158:159], v[158:159], 0, s[68:69]
	s_mov_b64 s[68:69], 0x180000
	s_add_i32 s41, s41, 2
	v_lshl_add_u64 v[160:161], v[160:161], 0, s[68:69]
	v_add_u32_e32 v170, 0x200, v170
	s_cmp_ge_u32 s59, s40
	s_mov_b32 s63, s58
	s_barrier
	s_cbranch_scc1 .LBB0_128

;     ...
;     auto compute = [&](int buf, int t) {
;         const LAS bf16* Ks = (const LAS bf16*)(lds + koff(buf)); const LAS bf16* VT = (const LAS bf16*)(lds + voff(buf));
;         bf16x8 kf[2][4]; float bias[2][2][4];
; #pragma unroll
;         for (int kb = 0; kb < 2; ++kb)
; #pragma unroll
;             for (int ks = 0; ks < 4; ++ks) kf[kb][ks] = *(const LAS bf16x8*)(Ks + (32 * kh + 16 * kb + fr) * QP + 32 * ks + 8 * fq);
;         if (MODE == 0) { const LAS float* bp = BT + (2047 - 16 - (q0 + 32 * rp + fr - t * 64 - 32 * kh - 4 * fq));
; #pragma unroll
;                 for (int kb = 0; kb < 2; ++kb)
; #pragma unroll
;                     for (int i = 0; i < 4; ++i) bias[0][kb][i] = bp[16 * (kb + 1) + i]; }
;         __builtin_amdgcn_sched_barrier(0);
;         f32x4 s[2][2];
; #pragma unroll
;         for (int rb = 0; rb < 2; ++rb)
; #pragma unroll
;             for (int kb = 0; kb < 2; ++kb) s[rb][kb] = (f32x4){0.f, 0.f, 0.f, 0.f};
;         bf16x8 pf[2];
;         auto smax = [&](int rb) {
;             if (MODE == 0) { s[rb][0] = s[rb][0] + (f32x4){bias[rb][0][0], bias[rb][0][1], bias[rb][0][2], bias[rb][0][3]}; s[rb][1] = s[rb][1] + (f32x4){bias[rb][1][0], bias[rb][1][1], bias[rb][1][2], bias[rb][1][3]}; }
;             else { s[rb][0] = s[rb][0] - bref; s[rb][1] = s[rb][1] - bref; }
;             float ps = 0.f;
; #pragma unroll
;             for (int kb = 0; kb < 2; ++kb)
; #pragma unroll
;                 for (int i = 0; i < 4; ++i) { s[rb][kb][i] = __builtin_amdgcn_exp2f(s[rb][kb][i]); ps += s[rb][kb][i]; }
;             lrun[rb] += ps;
;             u32x4 pw; pw.x = pk2(s[rb][0][0], s[rb][0][1]); pw.y = pk2(s[rb][0][2], s[rb][0][3]); pw.z = pk2(s[rb][1][0], s[rb][1][1]); pw.w = pk2(s[rb][1][2], s[rb][1][3]);
;             pf[rb] = __builtin_bit_cast(bf16x8, pw); };
; #pragma unroll
;         for (int ks = 0; ks < 4; ++ks)
; #pragma unroll
;             for (int kb = 0; kb < 2; ++kb) MMA16(kf[kb][ks], qf[0][ks], s[0][kb]);
;         __builtin_amdgcn_sched_barrier(0);
;         bf16x8 vf[8];
; #pragma unroll
;         for (int db = 0; db < 8; ++db) vf[db] = *(const LAS bf16x8*)(VT + (16 * db + fr) * VPA + 32 * kh + 8 * fq);
;         if (MODE == 0) { const LAS float* bp = BT + (2047 - 16 - (q0 + 32 * rp + fr - t * 64 - 32 * kh - 4 * fq));
; #pragma unroll
;             for (int kb = 0; kb < 2; ++kb)
; #pragma unroll
.LBB0_125:
	s_mul_i32 s78, s63, 0x9800
	s_add_i32 s79, s78, 0
	v_add_u32_e32 v171, s79, v165
	v_add_u32_e32 v182, v171, v167
	ds_read_b128 v[128:131], v182
	ds_read_b128 v[132:135], v182 offset:64
	ds_read_b128 v[136:139], v182 offset:128
	ds_read_b128 v[140:143], v182 offset:192
	ds_read_b128 v[144:147], v182 offset:4608
	ds_read_b128 v[172:175], v182 offset:4672
	ds_read_b128 v[192:195], v182 offset:4736
	ds_read_b128 v[196:199], v182 offset:4800
	ds_read2_b32 v[182:183], v170 offset0:16 offset1:17
	ds_read2_b32 v[184:185], v170 offset0:18 offset1:19
	ds_read2_b32 v[188:189], v170 offset0:32 offset1:33
	ds_read2_b32 v[190:191], v170 offset0:34 offset1:35
	s_waitcnt lgkmcnt(11)
	v_mfma_f32_16x16x32_bf16 v[200:203], v[128:131], v[76:79], 0
	s_waitcnt lgkmcnt(7)
	v_mfma_f32_16x16x32_bf16 v[204:207], v[144:147], v[76:79], 0
	v_mfma_f32_16x16x32_bf16 v[200:203], v[132:135], v[80:83], v[200:203]
	s_waitcnt lgkmcnt(6)
	v_mfma_f32_16x16x32_bf16 v[204:207], v[172:175], v[80:83], v[204:207]
	v_mfma_f32_16x16x32_bf16 v[200:203], v[136:139], v[84:87], v[200:203]
	s_waitcnt lgkmcnt(5)
	v_mfma_f32_16x16x32_bf16 v[204:207], v[192:195], v[84:87], v[204:207]
	v_mfma_f32_16x16x32_bf16 v[200:203], v[140:143], v[88:91], v[200:203]
	s_waitcnt lgkmcnt(4)
	v_mfma_f32_16x16x32_bf16 v[204:207], v[196:199], v[88:91], v[204:207]
	v_mfma_f32_16x16x32_bf16 v[128:131], v[128:131], v[92:95], 0
	ds_read2_b32 v[212:213], v170 offset1:1
	v_add3_u32 v171, v171, v168, v169
	s_waitcnt lgkmcnt(3)
	s_nop 1
	v_add_f32_e32 v184, v184, v202
	v_add_f32_e32 v185, v185, v203
	v_add_f32_e32 v182, v182, v200
	v_add_f32_e32 v183, v183, v201
	s_waitcnt lgkmcnt(1)
	v_add_f32_e32 v190, v190, v206
	v_add_f32_e32 v191, v191, v207
	v_mfma_f32_16x16x32_bf16 v[144:147], v[144:147], v[92:95], 0
	ds_read_b128 v[200:203], v171 offset:36352
	v_add_f32_e32 v188, v188, v204
	v_add_f32_e32 v189, v189, v205
	ds_read2_b32 v[224:225], v170 offset0:16 offset1:17
	v_mfma_f32_16x16x32_bf16 v[128:131], v[132:135], v[96:99], v[128:131]
	ds_read_b128 v[204:207], v171 offset:18432
	ds_read2_b32 v[226:227], v170 offset0:18 offset1:19
	ds_read_b128 v[216:219], v171 offset:33792
	v_mfma_f32_16x16x32_bf16 v[132:135], v[172:175], v[96:99], v[144:147]
	s_nop 2
	ds_read_b128 v[144:147], v171 offset:20992
	v_mfma_f32_16x16x32_bf16 v[128:131], v[136:139], v[100:103], v[128:131]
	ds_read_b128 v[172:175], v171 offset:23552
	v_exp_f32_e32 v139, v184
	v_exp_f32_e32 v137, v185
	v_mfma_f32_16x16x32_bf16 v[132:135], v[192:195], v[100:103], v[132:135]
	ds_read_b128 v[192:195], v171 offset:26112
	v_mfma_f32_16x16x32_bf16 v[128:131], v[140:143], v[104:107], v[128:131]
	ds_read_b128 v[208:211], v171 offset:28672
	v_exp_f32_e32 v143, v182
	v_exp_f32_e32 v141, v183
	s_waitcnt lgkmcnt(9)
	s_nop 3
	v_add_f32_e32 v220, v212, v128
	v_add_f32_e32 v221, v213, v129
	v_mfma_f32_16x16x32_bf16 v[196:199], v[196:199], v[104:107], v[132:135]
	ds_read2_b32 v[128:129], v170 offset0:2 offset1:3
	ds_read_b128 v[212:215], v171 offset:31232
	v_exp_f32_e32 v142, v220
	v_exp_f32_e32 v135, v188
	v_exp_f32_e32 v133, v189
	s_waitcnt lgkmcnt(1)
	v_add_f32_e32 v222, v128, v130
	v_add_f32_e32 v223, v129, v131
	s_nop 0
	v_add_f32_e32 v182, v226, v198
	v_add_f32_e32 v183, v227, v199
	v_add_f32_e32 v184, v224, v196
	v_add_f32_e32 v185, v225, v197
	v_exp_f32_e32 v131, v190
	v_exp_f32_e32 v129, v191
	v_exp_f32_e32 v140, v221
	v_exp_f32_e32 v138, v222
	v_exp_f32_e32 v136, v223
	v_exp_f32_e32 v134, v184
	v_exp_f32_e32 v132, v185
	v_exp_f32_e32 v130, v182
	v_exp_f32_e32 v128, v183
	v_cvt_pk_bf16_f32 v196, v143, v141
	v_cvt_pk_bf16_f32 v197, v139, v137
	v_cvt_pk_bf16_f32 v198, v135, v133
	v_cvt_pk_bf16_f32 v199, v131, v129
	s_nop 0
	v_mfma_f32_16x16x32_bf16 v[124:127], v[204:207], v[196:199], v[124:127]
	v_mfma_f32_16x16x32_bf16 v[120:123], v[144:147], v[196:199], v[120:123]
	v_mfma_f32_16x16x32_bf16 v[116:119], v[172:175], v[196:199], v[116:119]
	v_mfma_f32_16x16x32_bf16 v[112:115], v[192:195], v[196:199], v[112:115]
	v_mfma_f32_16x16x32_bf16 v[108:111], v[208:211], v[196:199], v[108:111]
	s_waitcnt lgkmcnt(0)
	v_mfma_f32_16x16x32_bf16 v[72:75], v[212:215], v[196:199], v[72:75]
	v_mfma_f32_16x16x32_bf16 v[68:71], v[216:219], v[196:199], v[68:71]
	v_mfma_f32_16x16x32_bf16 v[64:67], v[200:203], v[196:199], v[64:67]
	v_cvt_pk_bf16_f32 v196, v142, v140
	v_cvt_pk_bf16_f32 v197, v138, v136
	v_cvt_pk_bf16_f32 v198, v134, v132
	v_cvt_pk_bf16_f32 v199, v130, v128
	s_nop 0
	v_mfma_f32_16x16x32_bf16 v[28:31], v[204:207], v[196:199], v[28:31]
	v_mfma_f32_16x16x32_bf16 v[24:27], v[144:147], v[196:199], v[24:27]
	v_mfma_f32_16x16x32_bf16 v[20:23], v[172:175], v[196:199], v[20:23]
	v_mfma_f32_16x16x32_bf16 v[16:19], v[192:195], v[196:199], v[16:19]
	v_mfma_f32_16x16x32_bf16 v[12:15], v[208:211], v[196:199], v[12:15]
	v_mfma_f32_16x16x32_bf16 v[8:11], v[212:215], v[196:199], v[8:11]
	v_mfma_f32_16x16x32_bf16 v[4:7], v[216:219], v[196:199], v[4:7]
	v_mfma_f32_16x16x32_bf16 v[0:3], v[200:203], v[196:199], v[0:3]
	s_add_i32 s68, s41, -2
	s_cmp_ge_u32 s68, s40
	s_barrier
	s_cbranch_scc1 .LBB0_121
	v_add3_u32 v144, s79, v149, v152
	s_add_i32 s68, s41, -1
	s_cmp_ge_u32 s68, s40
	s_cbranch_scc1 .Lattn_b_short
	s_waitcnt vmcnt(7)
	ds_write_b128 v144, v[48:51]
	s_waitcnt vmcnt(6)
	ds_write_b128 v144, v[52:55] offset:128
	v_add3_u32 v144, s79, v157, v148
	s_waitcnt vmcnt(4)
	s_branch .Lattn_b_join
